# kv up-projection tiles redistributed 1 per low-rank / 3 per high-rank workgroup to balance against the q up-projection's 2 / 1 split (no seam between the two phases)
# speedup vs baseline: 1.0038x; 1.0038x over previous
;     __device__ bool next(int i, Unit& u) const {
;         if ((long)i * G + c >= nwg) return false;
;         const long L = (long)((rev && nwg % G == 0) ? (nwg / G - 1 - i) : i) * G + c;
;         int wgid = (int)L; { const int q = nwg / NXCD, r = nwg % NXCD, xcd = wgid % NXCD, off = wgid / NXCD; wgid = (xcd < r ? xcd * (q + 1) : r * (q + 1) + (xcd - r) * q) + off; }
;         const int nig = WGM * nN, gid = wgid / nig, fm = gid * WGM, gsz = (nM - fm) < WGM ? (nM - fm) : WGM;
;         u.pm = fm + ((wgid % nig) % gsz); u.pn = (wgid % nig) / gsz; return true;
.LBB0_665:
	s_add_i32 s88, s88, 1
	s_cmp_lg_u32 s69, 0x100
	s_cbranch_scc1 .Lkv_orig
	s_lshr_b32 s4, s68, 3
	s_cmp_lt_u32 s4, 16
	s_cselect_b32 s5, 1, 3
	s_cmp_lt_u32 s88, s5
	s_cselect_b64 s[42:43], -1, 0
	s_cbranch_scc0 .LBB0_671
	s_lshl_b32 s5, s88, 4
	s_add_i32 s4, s4, s5
	s_and_b32 s5, s68, 7
	s_lshl_b32 s56, s5, 6
	s_add_i32 s4, s56, s4
	s_branch .Lkv_join
.Lkv_orig:
	s_mul_i32 s4, s88, s91
	s_mul_hi_u32 s5, s88, s69
	s_add_i32 s41, s5, s4
	s_mul_i32 s40, s88, s69
	v_mov_b64_e32 v[2:3], s[54:55]
	v_cmp_ge_i64_e32 vcc, s[40:41], v[2:3]
	v_cmp_lt_i64_e64 s[42:43], s[40:41], v[2:3]
	s_cbranch_vccnz .LBB0_671
	s_mul_i32 s4, s88, s69
	s_add_i32 s4, s4, s68
	s_ashr_i32 s5, s4, 31
	s_lshr_b32 s5, s5, 29
	s_add_i32 s45, s4, s5
	s_and_b32 s5, s45, -8
	s_sub_i32 s48, s4, s5
	s_cmp_gt_i32 s48, -1
	s_mov_b64 s[40:41], -1
	s_cbranch_scc0 .LBB0_668
	s_lshl_b32 s56, s48, 6
	s_mov_b64 s[40:41], 0

;     __device__ bool next(int i, Unit& u) const {
;     ...
;         const int nig = WGM * nN, gid = wgid / nig, fm = gid * WGM, gsz = (nM - fm) < WGM ? (nM - fm) : WGM;
;         u.pm = fm + ((wgid % nig) % gsz); u.pn = (wgid % nig) / gsz; return true;
.Lkv_join:
	s_ashr_i32 s5, s4, 31
	s_lshr_b32 s5, s5, 27
	s_add_i32 s5, s4, s5
	s_ashr_i32 s40, s5, 5
	s_lshl_b32 s40, s40, 3
	s_sub_i32 s41, 0x80, s40
	s_min_i32 s41, s41, 8
	s_abs_i32 s45, s41
	v_cvt_f32_u32_e32 v0, s45
	s_sub_i32 s56, 0, s45
	s_andn2_b32 s5, s5, 31
	s_sub_i32 s4, s4, s5
	v_rcp_iflag_f32_e32 v0, v0
	s_abs_i32 s5, s4
	s_xor_b32 s48, s4, s41
	s_ashr_i32 s48, s48, 31
	v_mul_f32_e32 v0, 0x4f7ffffe, v0
	v_cvt_u32_f32_e32 v0, v0
	s_nop 0
	v_readfirstlane_b32 s57, v0
	s_mul_i32 s56, s56, s57
	s_mul_hi_u32 s56, s57, s56
	s_add_i32 s57, s57, s56
	s_mul_hi_u32 s56, s5, s57
	s_mul_i32 s57, s56, s45
	s_sub_i32 s5, s5, s57
	s_add_i32 s58, s56, 1
	s_sub_i32 s57, s5, s45
	s_cmp_ge_u32 s5, s45
	s_cselect_b32 s56, s58, s56
	s_cselect_b32 s5, s57, s5
	s_add_i32 s57, s56, 1
	s_cmp_ge_u32 s5, s45
	s_cselect_b32 s5, s57, s56
	s_xor_b32 s5, s5, s48
	s_sub_i32 s56, s5, s48
	s_mul_i32 s5, s56, s41
	s_sub_i32 s4, s4, s5
	s_add_i32 s92, s40, s4
